# MLA short query block visits key tiles in order 0,n-1..1 so the 8 blocks of a head share K/V tiles in L2 during their second call
# speedup vs baseline: 1.0081x; 1.0078x over previous
; DI void mla_block(const Params& p, LAS unsigned char* lds, int b, int hd, int qb, int tid) {
;     ...
;     for (int kt = 0; kt < ntiles; ++kt) {
;         asm volatile("s_waitcnt vmcnt(0)" ::: "memory");
;         __builtin_amdgcn_s_barrier();
;         asm volatile("" ::: "memory");
;         const int bprev = bcur == 0 ? 2 : bcur - 1, bnext = bcur == 2 ? 0 : bcur + 1;
;         if (kt + 1 < ntiles) MLA_STAGE(kt + 1, bnext);
.LBB0_724:
	s_add_i32 s76, s87, 1
	s_waitcnt vmcnt(0)
	s_barrier
	s_cmp_lg_u32 s87, 2
	s_cselect_b32 s76, s76, 0
	s_add_i32 s77, s88, 1
	s_sub_i32 s98, s73, s77
	s_sub_i32 s99, s73, s88
	s_cmp_eq_u32 s88, 0
	s_cselect_b32 s99, 0, s99
	s_cmp_eq_u32 s88, 1
	s_cselect_b32 s100, -1, s99
	s_cmp_ge_u32 s77, s73
	s_cbranch_scc1 .LBB0_737
	s_andn2_b64 vcc, exec, s[2:3]
	s_cbranch_vccnz .Lmla_toplate_1
	s_cmp_gt_i32 s99, s33
	s_cbranch_scc0 .LBB0_737
	s_branch .Lmla_stnow_1
.Lmla_toplate_1:
	s_cmp_eq_u32 s88, 0
	s_cbranch_scc1 .Lmla_stnow_1
	s_cmp_lt_i32 s100, s33
	s_cbranch_scc1 .LBB0_737
.Lmla_stnow_1:
	s_mul_i32 s89, s76, 0xac00
	s_andn2_b64 vcc, exec, s[80:81]
	s_add_i32 s89, s89, 0
	s_cbranch_vccnz .LBB0_731
	v_readlane_b32 s90, v255, 9
	v_lshl_add_u32 v0, s98, v176, v166
	s_add_i32 m0, s89, s90
	s_nop 0
	global_load_lds_dwordx4 v0, s[12:13]
	s_andn2_b64 vcc, exec, s[82:83]
	s_cbranch_vccz .LBB0_732

.LBB0_728:
	v_readlane_b32 s90, v255, 11
	v_lshl_add_u32 v0, s98, v178, v168
	s_add_i32 m0, s89, s90
	s_nop 0
	global_load_lds_dwordx4 v0, s[12:13]
	s_andn2_b64 vcc, exec, s[92:93]
	s_cbranch_vccz .LBB0_734

.LBB0_730:
	v_lshl_add_u32 v0, s98, v180, v170
	s_add_i32 m0, s89, s86
	s_nop 0
	global_load_lds_dwordx4 v0, s[12:13]
	s_andn2_b64 vcc, exec, s[94:95]
	s_cbranch_vccz .LBB0_736
	s_branch .LBB0_737

.LBB0_732:
	v_lshl_add_u32 v0, s98, v177, v167
	s_add_i32 m0, s89, s75
	s_nop 0
	global_load_lds_dwordx4 v0, s[12:13]
	s_andn2_b64 vcc, exec, s[96:97]
	s_cbranch_vccz .LBB0_728

.LBB0_734:
	v_readlane_b32 s90, v255, 49
	v_lshl_add_u32 v0, s98, v179, v169
	s_add_i32 m0, s89, s90
	s_nop 0
	global_load_lds_dwordx4 v0, s[12:13]
	s_andn2_b64 vcc, exec, s[70:71]
	s_cbranch_vccz .LBB0_730

; #define LAS __attribute__((address_space(3)))
; #define MFMA32(a, b, c) __builtin_amdgcn_mfma_f32_32x32x16_bf16((a), (b), (c), 0, 0, 0)
; DI void mla_pv(const LAS unsigned char* base, int r, int h, const bf16x8 (&pf0)[2], const bf16x8 (&pf1)[2], f32x16 (&o)[4]) {
;     const LAS unsigned char* vp = base + MLA_KBYTES + r * MLA_VROW + h * 32;
; #pragma unroll
;     for (int s = 0; s < 2; ++s) {
;         bf16x8 va[4], vb[4];
; #pragma unroll
;         for (int dt = 0; dt < 4; ++dt) { va[dt] = *(const LAS bf16x8*)(vp + dt * 32 * MLA_VROW + s * 16); vb[dt] = *(const LAS bf16x8*)(vp + dt * 32 * MLA_VROW + 64 + s * 16); }
;         __builtin_amdgcn_sched_barrier(0);
; #pragma unroll
;         for (int dt = 0; dt < 4; ++dt) o[dt] = MFMA32(va[dt], pf0[s], o[dt]);
; #pragma unroll
;         for (int dt = 0; dt < 4; ++dt) o[dt] = MFMA32(vb[dt], pf1[s], o[dt]);
;         __builtin_amdgcn_sched_barrier(0);
;     }
.LBB0_736:
	v_lshl_add_u32 v0, s98, v181, v171
	s_add_i32 m0, s89, s72
	s_nop 0
	global_load_lds_dwordx4 v0, s[12:13]
.LBB0_737:
	s_cmp_lg_u32 s88, 0
	s_cselect_b64 s[90:91], -1, 0
	s_and_b64 s[90:91], s[78:79], s[90:91]
	s_cmp_lt_i32 s100, s33
	s_cselect_b64 vcc, -1, 0
	s_and_b64 s[90:91], s[90:91], vcc
	s_andn2_b64 vcc, exec, s[90:91]
	s_mul_i32 s89, s87, 0xac00
	s_cbranch_vccnz .LBB0_740
	s_add_i32 s90, s89, 0xffff5400
	s_cmp_lg_u32 s87, 0
	s_cselect_b32 s87, s90, 0x15800
	v_add_u32_e32 v0, s87, v182
	ds_read_b128 v[84:87], v0 offset:25600
	ds_read_b128 v[88:91], v0 offset:25664
	ds_read_b128 v[92:95], v0 offset:30208
	ds_read_b128 v[96:99], v0 offset:30272
	ds_read_b128 v[100:103], v0 offset:34816
	ds_read_b128 v[104:107], v0 offset:34880
	ds_read_b128 v[108:111], v0 offset:39424
	ds_read_b128 v[186:189], v0 offset:39488
	ds_read_b128 v[200:203], v0 offset:25616
	ds_read_b128 v[204:207], v0 offset:25680
	ds_read_b128 v[208:211], v0 offset:30224
	ds_read_b128 v[212:215], v0 offset:30288
	ds_read_b128 v[216:219], v0 offset:34832
	ds_read_b128 v[220:223], v0 offset:34896
	ds_read_b128 v[224:227], v0 offset:39440
	ds_read_b128 v[228:231], v0 offset:39504
	s_cmp_ge_u32 s77, s73
	s_cbranch_scc1 .Lmla_pvplain_1
	s_mul_i32 s91, s76, 0xac00
	s_waitcnt lgkmcnt(8)
	v_mfma_f32_32x32x16_bf16 v[64:79], v[84:87], v[80:83], v[64:79]
	v_readlane_b32 s90, v255, 9
	v_lshl_add_u32 v253, s98, v176, v166
	s_add_i32 m0, s91, s90
	s_nop 0
	global_load_lds_dwordx4 v253, s[12:13]
	v_mfma_f32_32x32x16_bf16 v[48:63], v[92:95], v[80:83], v[48:63]
	v_mfma_f32_32x32x16_bf16 v[32:47], v[100:103], v[80:83], v[32:47]
	v_lshl_add_u32 v253, s98, v177, v167
	s_add_i32 m0, s91, s75
	s_nop 0
	global_load_lds_dwordx4 v253, s[12:13]
	v_mfma_f32_32x32x16_bf16 v[16:31], v[108:111], v[80:83], v[16:31]
	v_mfma_f32_32x32x16_bf16 v[64:79], v[88:91], v[6:9], v[64:79]
	v_readlane_b32 s90, v255, 11
	v_lshl_add_u32 v253, s98, v178, v168
	s_add_i32 m0, s91, s90
	s_nop 0
	global_load_lds_dwordx4 v253, s[12:13]
	v_mfma_f32_32x32x16_bf16 v[48:63], v[96:99], v[6:9], v[48:63]
	v_mfma_f32_32x32x16_bf16 v[32:47], v[104:107], v[6:9], v[32:47]
	v_readlane_b32 s90, v255, 49
	v_lshl_add_u32 v253, s98, v179, v169
	s_add_i32 m0, s91, s90
	s_nop 0
	global_load_lds_dwordx4 v253, s[12:13]
	v_mfma_f32_32x32x16_bf16 v[16:31], v[186:189], v[6:9], v[16:31]
	s_waitcnt lgkmcnt(0)
	v_mfma_f32_32x32x16_bf16 v[64:79], v[200:203], v[10:13], v[64:79]
	v_lshl_add_u32 v253, s98, v180, v170
	s_add_i32 m0, s91, s86
	s_nop 0
	global_load_lds_dwordx4 v253, s[12:13]
	v_mfma_f32_32x32x16_bf16 v[48:63], v[208:211], v[10:13], v[48:63]
	v_mfma_f32_32x32x16_bf16 v[32:47], v[216:219], v[10:13], v[32:47]
	s_andn2_b64 vcc, exec, s[94:95]
	s_cbranch_vccnz .Lmla_a5_pv_1
	v_lshl_add_u32 v253, s98, v181, v171
	s_add_i32 m0, s91, s72
	s_nop 0
	global_load_lds_dwordx4 v253, s[12:13]

; DI void mla_block(const Params& p, LAS unsigned char* lds, int b, int hd, int qb, int tid) {
;     ...
;         if (kt <= wlast) {
;             mla_s_softmax(lds + bcur * MLA_BUF, r, h, kt == wlast, q0 + r - kt * 64, qf, o, m_run, l_run, pf0, pf1);
.Lmla_pvdone_1:
	s_cmp_gt_i32 s99, s33
	s_cbranch_scc0 .LBB0_741

; #define LAS __attribute__((address_space(3)))
; DI f32x16 zero16() { f32x16 z; for (int i = 0; i < 16; ++i) z[i] = 0.f; return z; }
; #define MFMA32(a, b, c) __builtin_amdgcn_mfma_f32_32x32x16_bf16((a), (b), (c), 0, 0, 0)
; DI void mla_s_softmax(const LAS unsigned char* base, int r, int h, bool is_diag, int lim, const bf16x8 (&qf)[12], f32x16 (&o)[4], float& m_run, float& l_run,
;                       bf16x8 (&pf0)[2], bf16x8 (&pf1)[2]) {
;     f32x16 s0 = zero16(), s1 = zero16();
;     const LAS unsigned char* kp = base + r * MLA_KROW + h * 16;
; #pragma unroll
;     for (int g = 0; g < 3; ++g) {
;         bf16x8 fa[4], fb[4];
; #pragma unroll
;         for (int j = 0; j < 4; ++j) { fa[j] = *(const LAS bf16x8*)(kp + (4 * g + j) * 32); fb[j] = *(const LAS bf16x8*)(kp + 32 * MLA_KROW + (4 * g + j) * 32); }
;         __builtin_amdgcn_sched_barrier(0);
; #pragma unroll
;         for (int j = 0; j < 4; ++j) { s0 = MFMA32(fa[j], qf[4 * g + j], s0); s1 = MFMA32(fb[j], qf[4 * g + j], s1); }
;         __builtin_amdgcn_sched_barrier(0);
;     }
;     if (is_diag) {
; #pragma unroll
;         for (int i = 0; i < 16; ++i) { if (16 * h + i > lim) s0[i] = -1e30f; if (32 + 16 * h + i > lim) s1[i] = -1e30f; }
.LBB0_740:
	s_cmp_gt_i32 s99, s33
	s_cbranch_scc1 .LBB0_739
.LBB0_741:
	s_add_i32 s87, s89, 0
	v_add3_u32 v0, s87, v175, v162
	s_andn2_b64 vcc, exec, s[2:3]
	s_branch .Lmla_splain_1
	s_cmp_ge_u32 s77, s73
	s_cbranch_scc1 .Lmla_splain_1
	s_mul_i32 s91, s76, 0xac00
	ds_read_b128 v[2:5], v0
	ds_read_b128 v[6:9], v0 offset:32
	ds_read_b128 v[10:13], v0 offset:12800
	ds_read_b128 v[186:189], v0 offset:12832
	ds_read_b128 v[190:193], v0 offset:64
	ds_read_b128 v[194:197], v0 offset:96
	ds_read_b128 v[198:201], v0 offset:12864
	ds_read_b128 v[202:205], v0 offset:12896
	ds_read_b128 v[206:209], v0 offset:128
	ds_read_b128 v[210:213], v0 offset:160
	ds_read_b128 v[214:217], v0 offset:12928
	ds_read_b128 v[218:221], v0 offset:12960
	ds_read_b128 v[222:225], v0 offset:192
	ds_read_b128 v[226:229], v0 offset:224
	ds_read_b128 v[230:233], v0 offset:12992
	ds_read_b128 v[234:237], v0 offset:13024
	s_waitcnt lgkmcnt(8)
	v_mfma_f32_32x32x16_bf16 v[96:111], v[2:5], v[112:115], 0
	v_readlane_b32 s90, v255, 9
	v_lshl_add_u32 v253, s98, v176, v166
	s_add_i32 m0, s91, s90
	s_nop 0
	global_load_lds_dwordx4 v253, s[12:13]
	v_mfma_f32_32x32x16_bf16 v[80:95], v[10:13], v[112:115], 0
	v_mfma_f32_32x32x16_bf16 v[96:111], v[6:9], v[116:119], v[96:111]
	v_lshl_add_u32 v253, s98, v177, v167
	s_add_i32 m0, s91, s75
	s_nop 0
	global_load_lds_dwordx4 v253, s[12:13]
	v_mfma_f32_32x32x16_bf16 v[80:95], v[186:189], v[116:119], v[80:95]
	v_mfma_f32_32x32x16_bf16 v[96:111], v[190:193], v[120:123], v[96:111]
	v_readlane_b32 s90, v255, 11
	v_lshl_add_u32 v253, s98, v178, v168
	s_add_i32 m0, s91, s90
	s_nop 0
	global_load_lds_dwordx4 v253, s[12:13]
	v_mfma_f32_32x32x16_bf16 v[80:95], v[198:201], v[120:123], v[80:95]
	v_mfma_f32_32x32x16_bf16 v[96:111], v[194:197], v[124:127], v[96:111]
	v_readlane_b32 s90, v255, 49
	v_lshl_add_u32 v253, s98, v179, v169
	s_add_i32 m0, s91, s90
	s_nop 0
	global_load_lds_dwordx4 v253, s[12:13]
	v_mfma_f32_32x32x16_bf16 v[80:95], v[202:205], v[124:127], v[80:95]
	ds_read_b128 v[2:5], v0 offset:256
	ds_read_b128 v[6:9], v0 offset:288
	ds_read_b128 v[10:13], v0 offset:13056
	ds_read_b128 v[186:189], v0 offset:13088
	ds_read_b128 v[190:193], v0 offset:320
	ds_read_b128 v[194:197], v0 offset:352
	ds_read_b128 v[198:201], v0 offset:13120
	ds_read_b128 v[202:205], v0 offset:13152
	s_waitcnt lgkmcnt(8)
	v_mfma_f32_32x32x16_bf16 v[96:111], v[206:209], v[128:131], v[96:111]
	v_lshl_add_u32 v253, s98, v180, v170
	s_add_i32 m0, s91, s86
	s_nop 0
	global_load_lds_dwordx4 v253, s[12:13]
	v_mfma_f32_32x32x16_bf16 v[80:95], v[214:217], v[128:131], v[80:95]
	v_mfma_f32_32x32x16_bf16 v[96:111], v[210:213], v[132:135], v[96:111]
	s_andn2_b64 vcc, exec, s[94:95]
	s_cbranch_vccnz .Lmla_a5_s_1
	v_lshl_add_u32 v253, s98, v181, v171
	s_add_i32 m0, s91, s72
	s_nop 0
	global_load_lds_dwordx4 v253, s[12:13]
.Lmla_a5_s_1:
	v_mfma_f32_32x32x16_bf16 v[80:95], v[218:221], v[132:135], v[80:95]
	v_mfma_f32_32x32x16_bf16 v[96:111], v[222:225], v[136:139], v[96:111]
	v_mfma_f32_32x32x16_bf16 v[80:95], v[230:233], v[136:139], v[80:95]
	v_mfma_f32_32x32x16_bf16 v[96:111], v[226:229], v[140:143], v[96:111]
	v_mfma_f32_32x32x16_bf16 v[80:95], v[234:237], v[140:143], v[80:95]
	s_waitcnt lgkmcnt(0)
	v_mfma_f32_32x32x16_bf16 v[96:111], v[2:5], v[144:147], v[96:111]
	v_mfma_f32_32x32x16_bf16 v[80:95], v[10:13], v[144:147], v[80:95]
	v_mfma_f32_32x32x16_bf16 v[96:111], v[6:9], v[148:151], v[96:111]
	v_mfma_f32_32x32x16_bf16 v[80:95], v[186:189], v[148:151], v[80:95]
	v_mfma_f32_32x32x16_bf16 v[96:111], v[190:193], v[152:155], v[96:111]
	v_mfma_f32_32x32x16_bf16 v[80:95], v[198:201], v[152:155], v[80:95]
	v_mfma_f32_32x32x16_bf16 v[96:111], v[194:197], v[156:159], v[96:111]
	v_mfma_f32_32x32x16_bf16 v[80:95], v[202:205], v[156:159], v[80:95]
	s_cmp_lg_u32 s33, s99
	s_cbranch_scc1 .LBB0_743
	s_branch .Lmla_bb640_1
.Lmla_splain_1:
	ds_read_b128 v[2:5], v0
	ds_read_b128 v[6:9], v0 offset:32
	ds_read_b128 v[10:13], v0 offset:12800
	ds_read_b128 v[186:189], v0 offset:12832
	ds_read_b128 v[190:193], v0 offset:64
	ds_read_b128 v[194:197], v0 offset:96
	ds_read_b128 v[198:201], v0 offset:12864
	ds_read_b128 v[202:205], v0 offset:12896
	ds_read_b128 v[206:209], v0 offset:128
	ds_read_b128 v[210:213], v0 offset:160
	ds_read_b128 v[214:217], v0 offset:12928
	ds_read_b128 v[218:221], v0 offset:12960
	ds_read_b128 v[222:225], v0 offset:192
	ds_read_b128 v[226:229], v0 offset:224
	ds_read_b128 v[230:233], v0 offset:12992
	ds_read_b128 v[234:237], v0 offset:13024
	s_cmp_lg_u32 s33, s99
	s_waitcnt lgkmcnt(8)
	v_mfma_f32_32x32x16_bf16 v[96:111], v[2:5], v[112:115], 0
	v_mfma_f32_32x32x16_bf16 v[80:95], v[10:13], v[112:115], 0
	v_mfma_f32_32x32x16_bf16 v[96:111], v[6:9], v[116:119], v[96:111]
	v_mfma_f32_32x32x16_bf16 v[80:95], v[186:189], v[116:119], v[80:95]
	v_mfma_f32_32x32x16_bf16 v[96:111], v[190:193], v[120:123], v[96:111]
	v_mfma_f32_32x32x16_bf16 v[80:95], v[198:201], v[120:123], v[80:95]
	v_mfma_f32_32x32x16_bf16 v[96:111], v[194:197], v[124:127], v[96:111]
	v_mfma_f32_32x32x16_bf16 v[80:95], v[202:205], v[124:127], v[80:95]
	ds_read_b128 v[2:5], v0 offset:256
	ds_read_b128 v[6:9], v0 offset:288
	ds_read_b128 v[10:13], v0 offset:13056
	ds_read_b128 v[186:189], v0 offset:13088
	ds_read_b128 v[190:193], v0 offset:320
	ds_read_b128 v[194:197], v0 offset:352
	ds_read_b128 v[198:201], v0 offset:13120
	ds_read_b128 v[202:205], v0 offset:13152
	s_waitcnt lgkmcnt(8)
	v_mfma_f32_32x32x16_bf16 v[96:111], v[206:209], v[128:131], v[96:111]
	v_mfma_f32_32x32x16_bf16 v[80:95], v[214:217], v[128:131], v[80:95]
	v_mfma_f32_32x32x16_bf16 v[96:111], v[210:213], v[132:135], v[96:111]
	v_mfma_f32_32x32x16_bf16 v[80:95], v[218:221], v[132:135], v[80:95]
	v_mfma_f32_32x32x16_bf16 v[96:111], v[222:225], v[136:139], v[96:111]
	v_mfma_f32_32x32x16_bf16 v[80:95], v[230:233], v[136:139], v[80:95]
	v_mfma_f32_32x32x16_bf16 v[96:111], v[226:229], v[140:143], v[96:111]
	v_mfma_f32_32x32x16_bf16 v[80:95], v[234:237], v[140:143], v[80:95]
	s_waitcnt lgkmcnt(0)
	v_mfma_f32_32x32x16_bf16 v[96:111], v[2:5], v[144:147], v[96:111]
	v_mfma_f32_32x32x16_bf16 v[80:95], v[10:13], v[144:147], v[80:95]
	v_mfma_f32_32x32x16_bf16 v[96:111], v[6:9], v[148:151], v[96:111]
	v_mfma_f32_32x32x16_bf16 v[80:95], v[186:189], v[148:151], v[80:95]
	v_mfma_f32_32x32x16_bf16 v[96:111], v[190:193], v[152:155], v[96:111]
	v_mfma_f32_32x32x16_bf16 v[80:95], v[198:201], v[152:155], v[80:95]
	v_mfma_f32_32x32x16_bf16 v[96:111], v[194:197], v[156:159], v[96:111]
	v_mfma_f32_32x32x16_bf16 v[80:95], v[202:205], v[156:159], v[80:95]
	s_cbranch_scc1 .LBB0_743

; #define LAS __attribute__((address_space(3)))
; DI unsigned pk2(float lo, float hi) { f32x2 v = {lo, hi}; bf2_t r = __builtin_convertvector(v, bf2_t); return __builtin_bit_cast(unsigned, r); }
; #define MFMA32(a, b, c) __builtin_amdgcn_mfma_f32_32x32x16_bf16((a), (b), (c), 0, 0, 0)
; DI void mla_s_softmax(const LAS unsigned char* base, int r, int h, bool is_diag, int lim, const bf16x8 (&qf)[12], f32x16 (&o)[4], float& m_run, float& l_run,
;                       bf16x8 (&pf0)[2], bf16x8 (&pf1)[2]) {
;     ...
;     float ls = 0.f;
; #pragma unroll
;     for (int i = 0; i < 16; ++i) { s0[i] = __builtin_amdgcn_exp2f(s0[i] - m_run); s1[i] = __builtin_amdgcn_exp2f(s1[i] - m_run); ls += s0[i] + s1[i]; }
;     l_run += ls;
; #pragma unroll
;     for (int s = 0; s < 2; ++s) {
;         u32x4 a, c;
;         a.x = pk2(s0[8 * s + 0], s0[8 * s + 1]); a.y = pk2(s0[8 * s + 2], s0[8 * s + 3]); a.z = pk2(s0[8 * s + 4], s0[8 * s + 5]); a.w = pk2(s0[8 * s + 6], s0[8 * s + 7]);
;         c.x = pk2(s1[8 * s + 0], s1[8 * s + 1]); c.y = pk2(s1[8 * s + 2], s1[8 * s + 3]); c.z = pk2(s1[8 * s + 4], s1[8 * s + 5]); c.w = pk2(s1[8 * s + 6], s1[8 * s + 7]);
;         pf0[s] = __builtin_bit_cast(bf16x8, a); pf1[s] = __builtin_bit_cast(bf16x8, c);
;     }
; }
; DI void mla_pv(const LAS unsigned char* base, int r, int h, const bf16x8 (&pf0)[2], const bf16x8 (&pf1)[2], f32x16 (&o)[4]) {
;     const LAS unsigned char* vp = base + MLA_KBYTES + r * MLA_VROW + h * 32;
; #pragma unroll
;     for (int s = 0; s < 2; ++s) {
;         bf16x8 va[4], vb[4];
; #pragma unroll
;         for (int dt = 0; dt < 4; ++dt) { va[dt] = *(const LAS bf16x8*)(vp + dt * 32 * MLA_VROW + s * 16); vb[dt] = *(const LAS bf16x8*)(vp + dt * 32 * MLA_VROW + 64 + s * 16); }
;         __builtin_amdgcn_sched_barrier(0);
; #pragma unroll
;         for (int dt = 0; dt < 4; ++dt) o[dt] = MFMA32(va[dt], pf0[s], o[dt]);
; #pragma unroll
;         for (int dt = 0; dt < 4; ++dt) o[dt] = MFMA32(vb[dt], pf1[s], o[dt]);
;         __builtin_amdgcn_sched_barrier(0);
;     }
.LBB0_745:
	v_sub_f32_e32 v0, v96, v183
	v_exp_f32_e32 v15, v0
	v_sub_f32_e32 v0, v80, v183
	v_sub_f32_e32 v2, v98, v183
	v_exp_f32_e32 v185, v0
	v_sub_f32_e32 v0, v97, v183
	v_exp_f32_e32 v97, v2
	v_sub_f32_e32 v2, v82, v183
	v_exp_f32_e32 v187, v2
	v_sub_f32_e32 v2, v99, v183
	v_exp_f32_e32 v96, v2
	v_sub_f32_e32 v2, v83, v183
	v_exp_f32_e32 v98, v2
	v_sub_f32_e32 v2, v100, v183
	v_exp_f32_e32 v186, v2
	v_sub_f32_e32 v2, v84, v183
	v_exp_f32_e32 v189, v2
	v_sub_f32_e32 v2, v101, v183
	v_exp_f32_e32 v84, v2
	v_sub_f32_e32 v2, v85, v183
	v_exp_f32_e32 v100, v2
	v_sub_f32_e32 v2, v102, v183
	v_exp_f32_e32 v188, v2
	v_sub_f32_e32 v2, v86, v183
	v_exp_f32_e32 v191, v2
	v_sub_f32_e32 v2, v103, v183
	v_exp_f32_e32 v86, v2
	v_sub_f32_e32 v2, v87, v183
	v_exp_f32_e32 v102, v2
	v_sub_f32_e32 v2, v104, v183
	v_exp_f32_e32 v190, v2
	v_sub_f32_e32 v2, v88, v183
	v_exp_f32_e32 v193, v2
	v_sub_f32_e32 v2, v105, v183
	v_exp_f32_e32 v88, v2
	v_sub_f32_e32 v2, v89, v183
	v_exp_f32_e32 v104, v2
	v_sub_f32_e32 v2, v106, v183
	v_exp_f32_e32 v192, v2
	v_sub_f32_e32 v2, v90, v183
	v_exp_f32_e32 v195, v2
	v_sub_f32_e32 v2, v107, v183
	v_exp_f32_e32 v90, v2
	v_sub_f32_e32 v2, v91, v183
	v_exp_f32_e32 v106, v2
	v_sub_f32_e32 v2, v108, v183
	v_exp_f32_e32 v194, v2
	v_sub_f32_e32 v2, v92, v183
	v_exp_f32_e32 v197, v2
	v_sub_f32_e32 v2, v109, v183
	v_exp_f32_e32 v92, v2
	v_sub_f32_e32 v2, v93, v183
	v_exp_f32_e32 v108, v2
	v_sub_f32_e32 v2, v110, v183
	v_exp_f32_e32 v196, v2
	v_sub_f32_e32 v2, v94, v183
	v_exp_f32_e32 v198, v2
	v_sub_f32_e32 v2, v111, v183
	v_exp_f32_e32 v14, v0
	v_sub_f32_e32 v0, v81, v183
	v_exp_f32_e32 v94, v2
	v_sub_f32_e32 v2, v95, v183
	v_exp_f32_e32 v0, v0
	v_exp_f32_e32 v110, v2
	v_cvt_pk_bf16_f32 v80, v15, v14
	v_cvt_pk_bf16_f32 v81, v97, v96
	v_cvt_pk_bf16_f32 v82, v186, v84
	v_cvt_pk_bf16_f32 v83, v188, v86
	v_cvt_pk_bf16_f32 v6, v185, v0
	v_cvt_pk_bf16_f32 v7, v187, v98
	v_cvt_pk_bf16_f32 v8, v189, v100
	v_cvt_pk_bf16_f32 v9, v191, v102
	v_cvt_pk_bf16_f32 v10, v190, v88
	v_cvt_pk_bf16_f32 v11, v192, v90
	v_cvt_pk_bf16_f32 v12, v194, v92
	v_cvt_pk_bf16_f32 v13, v196, v94
	v_cvt_pk_bf16_f32 v2, v193, v104
	v_cvt_pk_bf16_f32 v3, v195, v106
	v_cvt_pk_bf16_f32 v4, v197, v108
	s_andn2_b64 vcc, exec, s[2:3]
	v_cvt_pk_bf16_f32 v5, v198, v110
	s_cbranch_vccnz .LBB0_747
	s_cmp_ge_u32 s77, s73
	s_cbranch_scc1 .Lmla_epv_plain_1
	s_mul_i32 s91, s76, 0xac00
	s_waitcnt lgkmcnt(0)
	v_mfma_f32_32x32x16_bf16 v[64:79], v[200:203], v[80:83], v[64:79]
	v_readlane_b32 s90, v255, 9
	v_lshl_add_u32 v253, s98, v176, v166
	s_add_i32 m0, s91, s90
	s_nop 0
	global_load_lds_dwordx4 v253, s[12:13]
	v_mfma_f32_32x32x16_bf16 v[48:63], v[208:211], v[80:83], v[48:63]
	v_mfma_f32_32x32x16_bf16 v[32:47], v[216:219], v[80:83], v[32:47]
	v_lshl_add_u32 v253, s98, v177, v167
	s_add_i32 m0, s91, s75
	s_nop 0
	global_load_lds_dwordx4 v253, s[12:13]
	v_mfma_f32_32x32x16_bf16 v[16:31], v[224:227], v[80:83], v[16:31]
	v_mfma_f32_32x32x16_bf16 v[64:79], v[204:207], v[6:9], v[64:79]
	v_readlane_b32 s90, v255, 11
	v_lshl_add_u32 v253, s98, v178, v168
	s_add_i32 m0, s91, s90
	s_nop 0
	global_load_lds_dwordx4 v253, s[12:13]
	v_mfma_f32_32x32x16_bf16 v[48:63], v[212:215], v[6:9], v[48:63]
	v_mfma_f32_32x32x16_bf16 v[32:47], v[220:223], v[6:9], v[32:47]
	v_readlane_b32 s90, v255, 49
	v_lshl_add_u32 v253, s98, v179, v169
	s_add_i32 m0, s91, s90
	s_nop 0
	global_load_lds_dwordx4 v253, s[12:13]
	v_mfma_f32_32x32x16_bf16 v[16:31], v[228:231], v[6:9], v[16:31]
	ds_read_b128 v[200:203], v252 offset:30288
	ds_read_b128 v[204:207], v252 offset:34896
	ds_read_b128 v[208:211], v252 offset:39504
	v_mfma_f32_32x32x16_bf16 v[64:79], v[232:235], v[10:13], v[64:79]
	v_lshl_add_u32 v253, s98, v180, v170
	s_add_i32 m0, s91, s86
	s_nop 0
	global_load_lds_dwordx4 v253, s[12:13]
	v_mfma_f32_32x32x16_bf16 v[48:63], v[236:239], v[10:13], v[48:63]
	v_mfma_f32_32x32x16_bf16 v[32:47], v[240:243], v[10:13], v[32:47]
	s_andn2_b64 vcc, exec, s[94:95]
	s_cbranch_vccnz .Lmla_a5_epv_1
	v_lshl_add_u32 v253, s98, v181, v171
	s_add_i32 m0, s91, s72
	s_nop 0
	global_load_lds_dwordx4 v253, s[12:13]

; #define LAS __attribute__((address_space(3)))
; #define MFMA32(a, b, c) __builtin_amdgcn_mfma_f32_32x32x16_bf16((a), (b), (c), 0, 0, 0)
; DI void mla_pv(const LAS unsigned char* base, int r, int h, const bf16x8 (&pf0)[2], const bf16x8 (&pf1)[2], f32x16 (&o)[4]) {
;     const LAS unsigned char* vp = base + MLA_KBYTES + r * MLA_VROW + h * 32;
; #pragma unroll
;     for (int s = 0; s < 2; ++s) {
;         bf16x8 va[4], vb[4];
; #pragma unroll
;         for (int dt = 0; dt < 4; ++dt) { va[dt] = *(const LAS bf16x8*)(vp + dt * 32 * MLA_VROW + s * 16); vb[dt] = *(const LAS bf16x8*)(vp + dt * 32 * MLA_VROW + 64 + s * 16); }
;         __builtin_amdgcn_sched_barrier(0);
; #pragma unroll
;         for (int dt = 0; dt < 4; ++dt) o[dt] = MFMA32(va[dt], pf0[s], o[dt]);
; #pragma unroll
;         for (int dt = 0; dt < 4; ++dt) o[dt] = MFMA32(vb[dt], pf1[s], o[dt]);
;         __builtin_amdgcn_sched_barrier(0);
;     }
; DI void mla_block(const Params& p, LAS unsigned char* lds, int b, int hd, int qb, int tid) {
;     ...
;     if (late && wlast == ntiles - 1) { const int bprev = bcur == 0 ? 2 : bcur - 1; mla_pv(lds + bprev * MLA_BUF, r, h, pf0, pf1, o); }
.LBB0_753:
	v_readlane_b32 s0, v255, 42
	s_or_b32 s0, s0, 3
	s_cmp_eq_u32 s33, s33
	s_cselect_b64 s[0:1], -1, 0
	s_and_b64 s[0:1], s[78:79], s[0:1]
	s_and_b64 vcc, exec, s[0:1]
	s_cbranch_vccz .LBB0_755
	s_mul_i32 s0, s76, 0xac00
	s_add_i32 s0, s0, 0xffff5400
	s_cmp_lg_u32 s76, 0
	s_cselect_b32 s0, s0, 0x15800
	s_add_i32 s0, s0, 0
	v_add3_u32 v0, s0, v173, v174
	ds_read_b128 v[84:87], v0 offset:25600
	ds_read_b128 v[88:91], v0 offset:25664
	ds_read_b128 v[92:95], v0 offset:30208
	ds_read_b128 v[96:99], v0 offset:30272
	ds_read_b128 v[100:103], v0 offset:34816
	ds_read_b128 v[104:107], v0 offset:34880
	ds_read_b128 v[108:111], v0 offset:39424
	ds_read_b128 v[112:115], v0 offset:39488
	s_waitcnt lgkmcnt(0)
	v_mfma_f32_32x32x16_bf16 v[64:79], v[84:87], v[80:83], v[64:79]
	v_mfma_f32_32x32x16_bf16 v[48:63], v[92:95], v[80:83], v[48:63]
	v_mfma_f32_32x32x16_bf16 v[32:47], v[100:103], v[80:83], v[32:47]
	v_mfma_f32_32x32x16_bf16 v[16:31], v[108:111], v[80:83], v[16:31]
	v_mfma_f32_32x32x16_bf16 v[64:79], v[88:91], v[6:9], v[64:79]
	v_mfma_f32_32x32x16_bf16 v[48:63], v[96:99], v[6:9], v[48:63]
	v_mfma_f32_32x32x16_bf16 v[32:47], v[104:107], v[6:9], v[32:47]
	v_mfma_f32_32x32x16_bf16 v[16:31], v[112:115], v[6:9], v[16:31]
	ds_read_b128 v[6:9], v0 offset:25616
	ds_read_b128 v[80:83], v0 offset:25680
	ds_read_b128 v[84:87], v0 offset:30224
	ds_read_b128 v[88:91], v0 offset:30288
	ds_read_b128 v[92:95], v0 offset:34832
	ds_read_b128 v[96:99], v0 offset:34896
	ds_read_b128 v[100:103], v0 offset:39440
	ds_read_b128 v[104:107], v0 offset:39504
	s_waitcnt lgkmcnt(0)
	v_mfma_f32_32x32x16_bf16 v[64:79], v[6:9], v[10:13], v[64:79]
	v_mfma_f32_32x32x16_bf16 v[48:63], v[84:87], v[10:13], v[48:63]
	v_mfma_f32_32x32x16_bf16 v[32:47], v[92:95], v[10:13], v[32:47]
	v_mfma_f32_32x32x16_bf16 v[16:31], v[100:103], v[10:13], v[16:31]
	v_mfma_f32_32x32x16_bf16 v[64:79], v[80:83], v[2:5], v[64:79]
	v_mfma_f32_32x32x16_bf16 v[48:63], v[88:91], v[2:5], v[48:63]
	v_mfma_f32_32x32x16_bf16 v[32:47], v[96:99], v[2:5], v[32:47]
	v_mfma_f32_32x32x16_bf16 v[16:31], v[104:107], v[2:5], v[16:31]

; __global__ void __launch_bounds__(512, 2) hymba_fwd(Params p) {
;     extern __shared__ __attribute__((aligned(16))) unsigned char lds_raw[];
	.amdhsa_kernel _Z9hymba_fwd6Params
		.amdhsa_group_segment_fixed_size 0
		.amdhsa_private_segment_fixed_size 0
		.amdhsa_kernarg_size 392
		.amdhsa_user_sgpr_count 2
		.amdhsa_user_sgpr_dispatch_ptr 0
		.amdhsa_user_sgpr_queue_ptr 0
		.amdhsa_user_sgpr_kernarg_segment_ptr 1
		.amdhsa_user_sgpr_dispatch_id 0
		.amdhsa_user_sgpr_kernarg_preload_length 0
		.amdhsa_user_sgpr_kernarg_preload_offset 0
		.amdhsa_user_sgpr_private_segment_size 0
		.amdhsa_uses_dynamic_stack 0
		.amdhsa_enable_private_segment 0
		.amdhsa_system_sgpr_workgroup_id_x 1
		.amdhsa_system_sgpr_workgroup_id_y 0
		.amdhsa_system_sgpr_workgroup_id_z 0
		.amdhsa_system_sgpr_workgroup_info 0
		.amdhsa_system_vgpr_workitem_id 2
		.amdhsa_next_free_vgpr 256
		.amdhsa_next_free_sgpr 102
		.amdhsa_accum_offset 256
		.amdhsa_reserve_vcc 1
		.amdhsa_float_round_mode_32 0
		.amdhsa_float_round_mode_16_64 0
		.amdhsa_float_denorm_mode_32 3
		.amdhsa_float_denorm_mode_16_64 3
		.amdhsa_dx10_clamp 1
		.amdhsa_ieee_mode 1
		.amdhsa_fp16_overflow 0
		.amdhsa_tg_split 0
		.amdhsa_exception_fp_ieee_invalid_op 0
		.amdhsa_exception_fp_denorm_src 0
		.amdhsa_exception_fp_ieee_div_zero 0
		.amdhsa_exception_fp_ieee_overflow 0
		.amdhsa_exception_fp_ieee_underflow 0
		.amdhsa_exception_fp_ieee_inexact 0
		.amdhsa_exception_int_div_zero 0
	.end_amdhsa_kernel

; __global__ void __launch_bounds__(512, 2) hymba_fwd(Params p) {
;     extern __shared__ __attribute__((aligned(16))) unsigned char lds_raw[];
amdhsa.kernels:
  - .agpr_count:     0
    .args:
      - .offset:         0
        .size:           136
        .value_kind:     by_value
      - .offset:         136
        .size:           4
        .value_kind:     hidden_block_count_x
      - .offset:         140
        .size:           4
        .value_kind:     hidden_block_count_y
      - .offset:         144
        .size:           4
        .value_kind:     hidden_block_count_z
      - .offset:         148
        .size:           2
        .value_kind:     hidden_group_size_x
      - .offset:         150
        .size:           2
        .value_kind:     hidden_group_size_y
      - .offset:         152
        .size:           2
        .value_kind:     hidden_group_size_z
      - .offset:         154
        .size:           2
        .value_kind:     hidden_remainder_x
      - .offset:         156
        .size:           2
        .value_kind:     hidden_remainder_y
      - .offset:         158
        .size:           2
        .value_kind:     hidden_remainder_z
      - .offset:         176
        .size:           8
        .value_kind:     hidden_global_offset_x
      - .offset:         184
        .size:           8
        .value_kind:     hidden_global_offset_y
      - .offset:         192
        .size:           8
        .value_kind:     hidden_global_offset_z
      - .offset:         200
        .size:           2
        .value_kind:     hidden_grid_dims
      - .offset:         224
        .size:           8
        .value_kind:     hidden_multigrid_sync_arg
      - .offset:         256
        .size:           4
        .value_kind:     hidden_dynamic_lds_size
    .group_segment_fixed_size: 0
    .kernarg_segment_align: 8
    .kernarg_segment_size: 392
    .language:       OpenCL C
    .language_version:
      - 2
      - 0
    .max_flat_workgroup_size: 512
    .name:           _Z9hymba_fwd6Params
    .private_segment_fixed_size: 0
    .sgpr_count:     108
    .sgpr_spill_count: 61
    .symbol:         _Z9hymba_fwd6Params.kd
    .uniform_work_group_size: 1
    .uses_dynamic_stack: false
    .vgpr_count:     256
    .vgpr_spill_count: 0
    .wavefront_size: 64
